# G2 q-projection epilogue: ssq row stats and rope table rows loaded in two batches up front instead of a load-wait round trip per (row, half) subgroup
# speedup vs baseline: 1.0165x; 1.0051x over previous
; __device__ __forceinline__ unsigned pkbf(float lo, float hi) { f2_t v = {lo, hi}; return __builtin_bit_cast(unsigned, __builtin_convertvector(v, bf2_t)); }
;     __device__ __forceinline__ void operator()(const f32x4 (&acc)[2][2][4][2], const Unit& u, int wr, int wc, int fr, int fq) const {
;         typedef unsigned u32x2 __attribute__((ext_vector_type(2)));
;         const int row0 = u.pm * BM + wr * 64 + fr;
; #pragma unroll
;         for (int ai = 0; ai < 2; ++ai)
; #pragma unroll
;             for (int m = 0; m < 4; ++m) { const int row = row0 + ai * HALF + m * 16; const int pos = row < 65536 ? (row & 2047) : 4096 + ((row - 65536) & 31);
; #pragma unroll
;                 for (int bj = 0; bj < 2; ++bj) { const int c0 = u.pn * BM + bj * HALF + wc * 32; f32x4 a = acc[ai][bj][m][0], b = acc[ai][bj][m][1];
;                     if ((c0 % 96) == 64) {
; #pragma unroll
;                         for (int j = 0; j < 4; ++j) { const f2_t cs = tab[pos * 16 + 4 * fq + j]; const float x1 = a[j], x2 = b[j]; a[j] = x1 * cs.x - x2 * cs.y; b[j] = x1 * cs.y + x2 * cs.x; } }
;                     { const float qs = qscale * rsqrtf(ssq[row] * (1.0f / 768.0f) + 1e-6f); a = a * qs; b = b * qs; }
;                     bf16_t* p = O + (size_t)row * 768 + c0 + 4 * fq;
;                     u32x2 wa, wb; wa.x = pkbf(a[0], a[1]); wa.y = pkbf(a[2], a[3]); wb.x = pkbf(b[0], b[1]); wb.y = pkbf(b[2], b[3]);
;                     *(u32x2*)p = wa; *(u32x2*)(p + 16) = wb; } }
.LBB0_125:
	s_lshl_b32 s0, s0, 8
	v_lshl_add_u32 v148, s1, 8, v141
	s_or_b32 s68, s0, s90
	s_mov_b32 s0, 0x10000
	v_cmp_gt_i32_e32 vcc, s0, v148
	s_mul_hi_i32 s0, s68, 0x2aaaaaab
	s_lshr_b32 s1, s0, 31
	s_lshr_b32 s0, s0, 4
	s_add_i32 s0, s0, s1
	v_and_b32_e32 v146, 0x7cf, v148
	s_mulk_i32 s0, 0x60
	v_cndmask_b32_e32 v146, v151, v146, vcc
	s_sub_i32 s0, s68, s0
	v_lshl_or_b32 v146, v146, 4, v140
	s_cmp_eq_u32 s0, 64
	s_cselect_b64 s[44:45], -1, 0
	s_cmp_lg_u32 s0, 64
	v_lshlrev_b32_e32 v154, 3, v146
	v_ashrrev_i32_e32 v243, 31, v148
	v_mov_b32_e32 v242, v148
	v_lshl_add_u64 v[240:241], v[242:243], 2, s[62:63]
	global_load_dword v192, v[240:241], off
	global_load_dword v193, v[240:241], off offset:64
	global_load_dword v194, v[240:241], off offset:128
	global_load_dword v195, v[240:241], off offset:192
	global_load_dword v196, v[240:241], off offset:512
	global_load_dword v197, v[240:241], off offset:576
	global_load_dword v198, v[240:241], off offset:640
	global_load_dword v199, v[240:241], off offset:704
	global_load_dwordx4 v[200:203], v154, s[4:5]
	global_load_dwordx4 v[204:207], v154, s[4:5] offset:16
	v_add_u32_e32 v236, 0x800, v154
	global_load_dwordx4 v[208:211], v236, s[4:5]
	global_load_dwordx4 v[212:215], v236, s[4:5] offset:16
	v_add_u32_e32 v237, 0x1000, v154
	global_load_dwordx4 v[216:219], v237, s[4:5]
	global_load_dwordx4 v[220:223], v237, s[4:5] offset:16
	v_add_u32_e32 v238, 0x1800, v154
	global_load_dwordx4 v[224:227], v238, s[4:5]
	global_load_dwordx4 v[228:231], v238, s[4:5] offset:16
	v_add_u32_e32 v239, 0x4000, v154
	s_waitcnt vmcnt(0)
	s_cbranch_scc1 .LBB0_127
	v_mov_b64_e32 v[156:157], v[200:201]
	v_mov_b64_e32 v[158:159], v[202:203]
	v_mov_b64_e32 v[160:161], v[204:205]
	v_mov_b64_e32 v[162:163], v[206:207]
	v_mov_b32_e32 v146, v156
	v_mov_b32_e32 v147, v158
	v_mov_b32_e32 v158, v157
	v_mul_f32_e32 v156, v126, v160
	v_mul_f32_e32 v164, v122, v161
	v_mul_f32_e32 v166, v126, v161
	v_mul_f32_e32 v160, v122, v160
	v_mov_b32_e32 v122, v127
	v_mov_b32_e32 v126, v123
	v_pk_mul_f32 v[168:169], v[120:121], v[158:159]
	v_pk_mul_f32 v[122:123], v[122:123], v[162:163]
	v_pk_mul_f32 v[126:127], v[126:127], v[162:163]
	v_pk_mul_f32 v[120:121], v[120:121], v[146:147]
	v_mov_b32_e32 v157, v122
	v_mov_b32_e32 v165, v123
	v_pk_fma_f32 v[146:147], v[124:125], v[146:147], v[168:169] neg_lo:[0,0,1] neg_hi:[0,0,1]
	v_mov_b32_e32 v167, v127
	v_mov_b32_e32 v161, v126
	v_pk_fma_f32 v[120:121], v[124:125], v[158:159], v[120:121]
	v_pk_add_f32 v[126:127], v[156:157], v[164:165] neg_lo:[0,1] neg_hi:[0,1]
	v_pk_add_f32 v[122:123], v[166:167], v[160:161]
	v_mov_b32_e32 v124, v146
	v_mov_b32_e32 v125, v147
.LBB0_127:
	v_ashrrev_i32_e32 v149, 31, v148
	v_lshl_add_u64 v[146:147], v[148:149], 2, s[62:63]
	s_ashr_i32 s69, s68, 31
	v_fmamk_f32 v149, v192, 0x3aaaaaab, v134
	v_cmp_gt_f32_e32 vcc, s13, v149
	v_mul_f32_e32 v155, 0x4b800000, v149
	s_nop 0
	v_cndmask_b32_e32 v149, v149, v155, vcc
	v_rsq_f32_e32 v149, v149
	s_nop 0
	v_mul_f32_e32 v155, 0x45800000, v149
	v_cndmask_b32_e32 v149, v149, v155, vcc
	v_mul_f32_e32 v156, 0x3e16c740, v149
	v_pk_mul_f32 v[126:127], v[126:127], v[156:157] op_sel_hi:[1,0]
	v_pk_mul_f32 v[124:125], v[124:125], v[156:157] op_sel_hi:[1,0]
	v_pk_mul_f32 v[122:123], v[122:123], v[156:157] op_sel_hi:[1,0]
	v_pk_mul_f32 v[156:157], v[120:121], v[156:157] op_sel_hi:[1,0]
	v_mov_b64_e32 v[120:121], s[60:61]
	v_mad_i64_i32 v[120:121], s[0:1], v148, s78, v[120:121]
	s_or_b32 s0, s68, 0x80
	s_mul_hi_i32 s1, s0, 0x2aaaaaab
	s_lshr_b32 s22, s1, 31
	s_lshr_b32 s1, s1, 4
	s_add_i32 s1, s1, s22
	s_mulk_i32 s1, 0x60
	s_sub_i32 s0, s0, s1
	v_lshl_add_u64 v[120:121], s[68:69], 1, v[120:121]
	s_cmp_eq_u32 s0, 64
	v_lshl_add_u64 v[120:121], v[120:121], 0, v[132:133]
	v_cvt_pk_bf16_f32 v124, v124, v125
	v_cvt_pk_bf16_f32 v125, v126, v127
	s_cselect_b64 s[46:47], -1, 0
	s_cmp_lg_u32 s0, 64
	v_cvt_pk_bf16_f32 v126, v156, v157
	v_cvt_pk_bf16_f32 v127, v122, v123
	global_store_dwordx2 v[120:121], v[124:125], off
	global_store_dwordx2 v[120:121], v[126:127], off offset:32
	s_cbranch_scc1 .LBB0_129
	v_mov_b64_e32 v[122:123], v[200:201]
	v_mov_b64_e32 v[124:125], v[202:203]
	s_nop 0
	v_mov_b64_e32 v[154:155], v[204:205]
	v_mov_b64_e32 v[156:157], v[206:207]
	v_mov_b32_e32 v126, v122
	v_mov_b32_e32 v127, v124
	v_mov_b32_e32 v124, v123
	v_mul_f32_e32 v122, v118, v154
	v_mul_f32_e32 v158, v114, v155
	v_mul_f32_e32 v160, v118, v155
	v_mul_f32_e32 v154, v114, v154
	v_mov_b32_e32 v114, v119
	v_mov_b32_e32 v118, v115
	v_pk_mul_f32 v[162:163], v[112:113], v[124:125]
	v_pk_mul_f32 v[114:115], v[114:115], v[156:157]
	v_pk_mul_f32 v[118:119], v[118:119], v[156:157]
	v_pk_mul_f32 v[112:113], v[112:113], v[126:127]
	v_mov_b32_e32 v123, v114
	v_mov_b32_e32 v159, v115
	v_pk_fma_f32 v[126:127], v[116:117], v[126:127], v[162:163] neg_lo:[0,0,1] neg_hi:[0,0,1]
	v_mov_b32_e32 v161, v119
	v_mov_b32_e32 v155, v118
	v_pk_fma_f32 v[112:113], v[116:117], v[124:125], v[112:113]
	v_pk_add_f32 v[118:119], v[122:123], v[158:159] neg_lo:[0,1] neg_hi:[0,1]
	v_pk_add_f32 v[114:115], v[160:161], v[154:155]
	v_mov_b32_e32 v116, v126
	v_mov_b32_e32 v117, v127
; __device__ __forceinline__ unsigned pkbf(float lo, float hi) { f2_t v = {lo, hi}; return __builtin_bit_cast(unsigned, __builtin_convertvector(v, bf2_t)); }
;     __device__ __forceinline__ void operator()(const f32x4 (&acc)[2][2][4][2], const Unit& u, int wr, int wc, int fr, int fq) const {
;     ...
;             for (int m = 0; m < 4; ++m) { const int row = row0 + ai * HALF + m * 16; const int pos = row < 65536 ? (row & 2047) : 4096 + ((row - 65536) & 31);
; #pragma unroll
;                 for (int bj = 0; bj < 2; ++bj) { const int c0 = u.pn * BM + bj * HALF + wc * 32; f32x4 a = acc[ai][bj][m][0], b = acc[ai][bj][m][1];
;                     if ((c0 % 96) == 64) {
; #pragma unroll
;                         for (int j = 0; j < 4; ++j) { const f2_t cs = tab[pos * 16 + 4 * fq + j]; const float x1 = a[j], x2 = b[j]; a[j] = x1 * cs.x - x2 * cs.y; b[j] = x1 * cs.y + x2 * cs.x; } }
;                     { const float qs = qscale * rsqrtf(ssq[row] * (1.0f / 768.0f) + 1e-6f); a = a * qs; b = b * qs; }
;                     bf16_t* p = O + (size_t)row * 768 + c0 + 4 * fq;
;                     u32x2 wa, wb; wa.x = pkbf(a[0], a[1]); wa.y = pkbf(a[2], a[3]); wb.x = pkbf(b[0], b[1]); wb.y = pkbf(b[2], b[3]);
;                     *(u32x2*)p = wa; *(u32x2*)(p + 16) = wb; } }
.LBB0_129:
	s_mov_b32 s0, 0x10000
	v_fmamk_f32 v122, v192, 0x3aaaaaab, v134
	v_cmp_gt_f32_e32 vcc, s13, v122
	v_mul_f32_e32 v123, 0x4b800000, v122
	s_nop 0
	v_cndmask_b32_e32 v122, v122, v123, vcc
	v_rsq_f32_e32 v122, v122
	s_nop 0
	v_mul_f32_e32 v123, 0x45800000, v122
	v_cndmask_b32_e32 v122, v122, v123, vcc
	v_mul_f32_e32 v122, 0x3e16c740, v122
	v_pk_mul_f32 v[114:115], v[114:115], v[122:123] op_sel_hi:[1,0]
	v_pk_mul_f32 v[112:113], v[112:113], v[122:123] op_sel_hi:[1,0]
	v_pk_mul_f32 v[118:119], v[118:119], v[122:123] op_sel_hi:[1,0]
	v_pk_mul_f32 v[116:117], v[116:117], v[122:123] op_sel_hi:[1,0]
	v_cvt_pk_bf16_f32 v112, v112, v113
	v_cvt_pk_bf16_f32 v113, v114, v115
	v_or_b32_e32 v114, 16, v148
	v_cvt_pk_bf16_f32 v116, v116, v117
	v_cvt_pk_bf16_f32 v117, v118, v119
	v_cmp_gt_i32_e32 vcc, s0, v114
	s_movk_i32 s0, 0x7df
	global_store_dwordx2 v[120:121], v[116:117], off offset:256
	global_store_dwordx2 v[120:121], v[112:113], off offset:288
	v_bitop3_b32 v112, v148, s0, 16 bitop3:0xc8
	v_cndmask_b32_e32 v112, v152, v112, vcc
	v_lshl_or_b32 v112, v112, 4, v140
	v_cndmask_b32_e64 v113, 0, 1, s[44:45]
	v_cmp_ne_u32_e64 s[42:43], 1, v113
	s_andn2_b64 vcc, exec, s[44:45]
	v_lshlrev_b32_e32 v116, 3, v112
	s_cbranch_vccnz .LBB0_131
	v_mov_b64_e32 v[118:119], v[208:209]
	v_mov_b64_e32 v[120:121], v[210:211]
	v_mov_b64_e32 v[122:123], v[212:213]
	v_mov_b64_e32 v[124:125], v[214:215]
	v_mov_b32_e32 v112, v118
	v_mov_b32_e32 v113, v120
	v_mov_b32_e32 v120, v119
	v_mul_f32_e32 v118, v110, v122
	v_mul_f32_e32 v126, v106, v123
	v_mul_f32_e32 v154, v110, v123
	v_mul_f32_e32 v122, v106, v122
	v_mov_b32_e32 v106, v111
	v_mov_b32_e32 v110, v107
	v_pk_mul_f32 v[156:157], v[104:105], v[120:121]
	v_pk_mul_f32 v[106:107], v[106:107], v[124:125]
	v_pk_mul_f32 v[110:111], v[110:111], v[124:125]
	v_pk_mul_f32 v[104:105], v[104:105], v[112:113]
	v_mov_b32_e32 v119, v106
	v_mov_b32_e32 v127, v107
	v_pk_fma_f32 v[112:113], v[108:109], v[112:113], v[156:157] neg_lo:[0,0,1] neg_hi:[0,0,1]
	v_mov_b32_e32 v155, v111
	v_mov_b32_e32 v123, v110
	v_pk_fma_f32 v[104:105], v[108:109], v[120:121], v[104:105]
	v_pk_add_f32 v[110:111], v[118:119], v[126:127] neg_lo:[0,1] neg_hi:[0,1]
	v_pk_add_f32 v[106:107], v[154:155], v[122:123]
	v_mov_b32_e32 v108, v112
	v_mov_b32_e32 v109, v113
.LBB0_131:
	v_ashrrev_i32_e32 v115, 31, v114
	v_lshl_add_u64 v[112:113], v[114:115], 2, s[62:63]
	v_fmamk_f32 v115, v193, 0x3aaaaaab, v134
	v_cmp_gt_f32_e32 vcc, s13, v115
	v_mul_f32_e32 v117, 0x4b800000, v115
	s_nop 0
	v_cndmask_b32_e32 v115, v115, v117, vcc
	v_rsq_f32_e32 v115, v115
	s_nop 0
	v_mul_f32_e32 v117, 0x45800000, v115
	v_cndmask_b32_e32 v115, v115, v117, vcc
	v_mul_f32_e32 v118, 0x3e16c740, v115
	v_pk_mul_f32 v[110:111], v[110:111], v[118:119] op_sel_hi:[1,0]
	v_pk_mul_f32 v[108:109], v[108:109], v[118:119] op_sel_hi:[1,0]
	v_pk_mul_f32 v[106:107], v[106:107], v[118:119] op_sel_hi:[1,0]
	v_pk_mul_f32 v[118:119], v[104:105], v[118:119] op_sel_hi:[1,0]
	v_mov_b64_e32 v[104:105], s[60:61]
	v_mad_i64_i32 v[104:105], s[0:1], v114, s78, v[104:105]
	v_lshl_add_u64 v[104:105], s[68:69], 1, v[104:105]
	v_cvt_pk_bf16_f32 v108, v108, v109
	v_cvt_pk_bf16_f32 v109, v110, v111
	v_cvt_pk_bf16_f32 v111, v106, v107
	v_cndmask_b32_e64 v106, 0, 1, s[46:47]
	v_lshl_add_u64 v[104:105], v[104:105], 0, v[132:133]
	v_cmp_ne_u32_e64 s[44:45], 1, v106
	s_andn2_b64 vcc, exec, s[46:47]
	v_cvt_pk_bf16_f32 v110, v118, v119
	global_store_dwordx2 v[104:105], v[108:109], off
	global_store_dwordx2 v[104:105], v[110:111], off offset:32
	s_cbranch_vccnz .LBB0_133
	v_mov_b64_e32 v[106:107], v[208:209]
	v_mov_b64_e32 v[108:109], v[210:211]
	s_nop 0
	v_mov_b64_e32 v[114:115], v[212:213]
	v_mov_b64_e32 v[116:117], v[214:215]
	v_mov_b32_e32 v110, v106
	v_mov_b32_e32 v111, v108
	v_mov_b32_e32 v108, v107
	v_mul_f32_e32 v106, v102, v114
	v_mul_f32_e32 v118, v98, v115
	v_mul_f32_e32 v120, v102, v115
	v_mul_f32_e32 v114, v98, v114
	v_mov_b32_e32 v98, v103
	v_mov_b32_e32 v102, v99
	v_pk_mul_f32 v[122:123], v[96:97], v[108:109]
	v_pk_mul_f32 v[98:99], v[98:99], v[116:117]
	v_pk_mul_f32 v[102:103], v[102:103], v[116:117]
	v_pk_mul_f32 v[96:97], v[96:97], v[110:111]
	v_mov_b32_e32 v107, v98
	v_mov_b32_e32 v119, v99
	v_pk_fma_f32 v[110:111], v[100:101], v[110:111], v[122:123] neg_lo:[0,0,1] neg_hi:[0,0,1]
	v_mov_b32_e32 v121, v103
	v_mov_b32_e32 v115, v102
	v_pk_fma_f32 v[96:97], v[100:101], v[108:109], v[96:97]
	v_pk_add_f32 v[102:103], v[106:107], v[118:119] neg_lo:[0,1] neg_hi:[0,1]
	v_pk_add_f32 v[98:99], v[120:121], v[114:115]
	v_mov_b32_e32 v100, v110
	v_mov_b32_e32 v101, v111
.LBB0_133:
	s_mov_b32 s0, 0x10000
	v_fmamk_f32 v106, v193, 0x3aaaaaab, v134
	v_cmp_gt_f32_e32 vcc, s13, v106
	v_mul_f32_e32 v107, 0x4b800000, v106
	s_nop 0
	v_cndmask_b32_e32 v106, v106, v107, vcc
	v_rsq_f32_e32 v106, v106
	s_nop 0
	v_mul_f32_e32 v107, 0x45800000, v106
	v_cndmask_b32_e32 v106, v106, v107, vcc
	v_mul_f32_e32 v106, 0x3e16c740, v106
	v_pk_mul_f32 v[98:99], v[98:99], v[106:107] op_sel_hi:[1,0]
	v_pk_mul_f32 v[96:97], v[96:97], v[106:107] op_sel_hi:[1,0]
	v_pk_mul_f32 v[102:103], v[102:103], v[106:107] op_sel_hi:[1,0]
	v_pk_mul_f32 v[100:101], v[100:101], v[106:107] op_sel_hi:[1,0]
	v_cvt_pk_bf16_f32 v96, v96, v97
	v_cvt_pk_bf16_f32 v97, v98, v99
	v_or_b32_e32 v98, 32, v148
	v_cvt_pk_bf16_f32 v100, v100, v101
	v_cvt_pk_bf16_f32 v101, v102, v103
	v_cmp_gt_i32_e32 vcc, s0, v98
	s_movk_i32 s0, 0x7ef
	global_store_dwordx2 v[104:105], v[100:101], off offset:256
	global_store_dwordx2 v[104:105], v[96:97], off offset:288
	v_bitop3_b32 v96, v148, s0, 32 bitop3:0xc8
	v_cndmask_b32_e32 v96, v151, v96, vcc
	v_lshl_or_b32 v96, v96, 4, v140
	s_and_b64 vcc, exec, s[42:43]
	v_lshlrev_b32_e32 v100, 3, v96
	s_cbranch_vccnz .LBB0_135
	v_mov_b64_e32 v[102:103], v[216:217]
	v_mov_b64_e32 v[104:105], v[218:219]
	v_mov_b64_e32 v[106:107], v[220:221]
	v_mov_b64_e32 v[108:109], v[222:223]
	v_mov_b32_e32 v96, v102
	v_mov_b32_e32 v97, v104
	v_mov_b32_e32 v104, v103
	v_mul_f32_e32 v102, v94, v106
	v_mul_f32_e32 v110, v90, v107
	v_mul_f32_e32 v112, v94, v107
	v_mul_f32_e32 v106, v90, v106
	v_mov_b32_e32 v90, v95
	v_mov_b32_e32 v94, v91
	v_pk_mul_f32 v[114:115], v[88:89], v[104:105]
	v_pk_mul_f32 v[90:91], v[90:91], v[108:109]
	v_pk_mul_f32 v[94:95], v[94:95], v[108:109]
	v_pk_mul_f32 v[88:89], v[88:89], v[96:97]
	v_mov_b32_e32 v103, v90
	v_mov_b32_e32 v111, v91
	v_pk_fma_f32 v[96:97], v[92:93], v[96:97], v[114:115] neg_lo:[0,0,1] neg_hi:[0,0,1]
	v_mov_b32_e32 v113, v95
	v_mov_b32_e32 v107, v94
	v_pk_fma_f32 v[88:89], v[92:93], v[104:105], v[88:89]
	v_pk_add_f32 v[94:95], v[102:103], v[110:111] neg_lo:[0,1] neg_hi:[0,1]
	v_pk_add_f32 v[90:91], v[112:113], v[106:107]
	v_mov_b32_e32 v92, v96
	v_mov_b32_e32 v93, v97
; __device__ __forceinline__ unsigned pkbf(float lo, float hi) { f2_t v = {lo, hi}; return __builtin_bit_cast(unsigned, __builtin_convertvector(v, bf2_t)); }
;     __device__ __forceinline__ void operator()(const f32x4 (&acc)[2][2][4][2], const Unit& u, int wr, int wc, int fr, int fq) const {
;     ...
;             for (int m = 0; m < 4; ++m) { const int row = row0 + ai * HALF + m * 16; const int pos = row < 65536 ? (row & 2047) : 4096 + ((row - 65536) & 31);
; #pragma unroll
;                 for (int bj = 0; bj < 2; ++bj) { const int c0 = u.pn * BM + bj * HALF + wc * 32; f32x4 a = acc[ai][bj][m][0], b = acc[ai][bj][m][1];
;                     if ((c0 % 96) == 64) {
; #pragma unroll
;                         for (int j = 0; j < 4; ++j) { const f2_t cs = tab[pos * 16 + 4 * fq + j]; const float x1 = a[j], x2 = b[j]; a[j] = x1 * cs.x - x2 * cs.y; b[j] = x1 * cs.y + x2 * cs.x; } }
;                     { const float qs = qscale * rsqrtf(ssq[row] * (1.0f / 768.0f) + 1e-6f); a = a * qs; b = b * qs; }
;                     bf16_t* p = O + (size_t)row * 768 + c0 + 4 * fq;
;                     u32x2 wa, wb; wa.x = pkbf(a[0], a[1]); wa.y = pkbf(a[2], a[3]); wb.x = pkbf(b[0], b[1]); wb.y = pkbf(b[2], b[3]);
;                     *(u32x2*)p = wa; *(u32x2*)(p + 16) = wb; } }
.LBB0_135:
	v_ashrrev_i32_e32 v99, 31, v98
	v_lshl_add_u64 v[96:97], v[98:99], 2, s[62:63]
	v_fmamk_f32 v99, v194, 0x3aaaaaab, v134
	v_cmp_gt_f32_e32 vcc, s13, v99
	v_mul_f32_e32 v101, 0x4b800000, v99
	s_nop 0
	v_cndmask_b32_e32 v99, v99, v101, vcc
	v_rsq_f32_e32 v99, v99
	s_nop 0
	v_mul_f32_e32 v101, 0x45800000, v99
	v_cndmask_b32_e32 v99, v99, v101, vcc
	v_mul_f32_e32 v102, 0x3e16c740, v99
	v_pk_mul_f32 v[94:95], v[94:95], v[102:103] op_sel_hi:[1,0]
	v_pk_mul_f32 v[92:93], v[92:93], v[102:103] op_sel_hi:[1,0]
	v_pk_mul_f32 v[90:91], v[90:91], v[102:103] op_sel_hi:[1,0]
	v_pk_mul_f32 v[102:103], v[88:89], v[102:103] op_sel_hi:[1,0]
	v_mov_b64_e32 v[88:89], s[60:61]
	v_mad_i64_i32 v[88:89], s[0:1], v98, s78, v[88:89]
	v_lshl_add_u64 v[88:89], s[68:69], 1, v[88:89]
	v_lshl_add_u64 v[88:89], v[88:89], 0, v[132:133]
	v_cvt_pk_bf16_f32 v92, v92, v93
	v_cvt_pk_bf16_f32 v93, v94, v95
	s_and_b64 vcc, exec, s[44:45]
	v_cvt_pk_bf16_f32 v94, v102, v103
	v_cvt_pk_bf16_f32 v95, v90, v91
	global_store_dwordx2 v[88:89], v[92:93], off
	global_store_dwordx2 v[88:89], v[94:95], off offset:32
	s_cbranch_vccnz .LBB0_137
	v_mov_b64_e32 v[90:91], v[216:217]
	v_mov_b64_e32 v[92:93], v[218:219]
	s_nop 0
	v_mov_b64_e32 v[98:99], v[220:221]
	v_mov_b64_e32 v[100:101], v[222:223]
	v_mov_b32_e32 v94, v90
	v_mov_b32_e32 v95, v92
	v_mov_b32_e32 v92, v91
	v_mul_f32_e32 v90, v86, v98
	v_mul_f32_e32 v102, v82, v99
	v_mul_f32_e32 v104, v86, v99
	v_mul_f32_e32 v98, v82, v98
	v_mov_b32_e32 v82, v87
	v_mov_b32_e32 v86, v83
	v_pk_mul_f32 v[106:107], v[80:81], v[92:93]
	v_pk_mul_f32 v[82:83], v[82:83], v[100:101]
	v_pk_mul_f32 v[86:87], v[86:87], v[100:101]
	v_pk_mul_f32 v[80:81], v[80:81], v[94:95]
	v_mov_b32_e32 v91, v82
	v_mov_b32_e32 v103, v83
	v_pk_fma_f32 v[94:95], v[84:85], v[94:95], v[106:107] neg_lo:[0,0,1] neg_hi:[0,0,1]
	v_mov_b32_e32 v105, v87
	v_mov_b32_e32 v99, v86
	v_pk_fma_f32 v[80:81], v[84:85], v[92:93], v[80:81]
	v_pk_add_f32 v[86:87], v[90:91], v[102:103] neg_lo:[0,1] neg_hi:[0,1]
	v_pk_add_f32 v[82:83], v[104:105], v[98:99]
	v_mov_b32_e32 v84, v94
	v_mov_b32_e32 v85, v95
.LBB0_137:
	s_mov_b32 s0, 0x10000
	v_fmamk_f32 v90, v194, 0x3aaaaaab, v134
	v_cmp_gt_f32_e32 vcc, s13, v90
	v_mul_f32_e32 v91, 0x4b800000, v90
	s_nop 0
	v_cndmask_b32_e32 v90, v90, v91, vcc
	v_rsq_f32_e32 v90, v90
	s_nop 0
	v_mul_f32_e32 v91, 0x45800000, v90
	v_cndmask_b32_e32 v90, v90, v91, vcc
	v_mul_f32_e32 v90, 0x3e16c740, v90
	v_pk_mul_f32 v[82:83], v[82:83], v[90:91] op_sel_hi:[1,0]
	v_pk_mul_f32 v[80:81], v[80:81], v[90:91] op_sel_hi:[1,0]
	v_pk_mul_f32 v[86:87], v[86:87], v[90:91] op_sel_hi:[1,0]
	v_pk_mul_f32 v[84:85], v[84:85], v[90:91] op_sel_hi:[1,0]
	v_cvt_pk_bf16_f32 v80, v80, v81
	v_cvt_pk_bf16_f32 v81, v82, v83
	v_or_b32_e32 v82, 48, v148
	v_cvt_pk_bf16_f32 v84, v84, v85
	v_cvt_pk_bf16_f32 v85, v86, v87
	v_cmp_gt_i32_e32 vcc, s0, v82
	s_movk_i32 s0, 0x7ff
	global_store_dwordx2 v[88:89], v[84:85], off offset:256
	global_store_dwordx2 v[88:89], v[80:81], off offset:288
	v_bitop3_b32 v80, v148, s0, 48 bitop3:0xc8
	v_cndmask_b32_e32 v80, v152, v80, vcc
	v_lshl_or_b32 v80, v80, 4, v140
	s_and_b64 vcc, exec, s[42:43]
	v_lshlrev_b32_e32 v84, 3, v80
	s_cbranch_vccnz .LBB0_139
	v_mov_b64_e32 v[86:87], v[224:225]
	v_mov_b64_e32 v[88:89], v[226:227]
	v_mov_b64_e32 v[90:91], v[228:229]
	v_mov_b64_e32 v[92:93], v[230:231]
	v_mov_b32_e32 v80, v86
	v_mov_b32_e32 v81, v88
	v_mov_b32_e32 v88, v87
	v_mul_f32_e32 v86, v78, v90
	v_mul_f32_e32 v94, v74, v91
	v_mul_f32_e32 v96, v78, v91
	v_mul_f32_e32 v90, v74, v90
	v_mov_b32_e32 v74, v79
	v_mov_b32_e32 v78, v75
	v_pk_mul_f32 v[98:99], v[72:73], v[88:89]
	v_pk_mul_f32 v[74:75], v[74:75], v[92:93]
	v_pk_mul_f32 v[78:79], v[78:79], v[92:93]
	v_pk_mul_f32 v[72:73], v[72:73], v[80:81]
	v_mov_b32_e32 v87, v74
	v_mov_b32_e32 v95, v75
	v_pk_fma_f32 v[80:81], v[76:77], v[80:81], v[98:99] neg_lo:[0,0,1] neg_hi:[0,0,1]
	v_mov_b32_e32 v97, v79
	v_mov_b32_e32 v91, v78
	v_pk_fma_f32 v[72:73], v[76:77], v[88:89], v[72:73]
	v_pk_add_f32 v[78:79], v[86:87], v[94:95] neg_lo:[0,1] neg_hi:[0,1]
	v_pk_add_f32 v[74:75], v[96:97], v[90:91]
	v_mov_b32_e32 v76, v80
	v_mov_b32_e32 v77, v81
.LBB0_139:
	v_ashrrev_i32_e32 v83, 31, v82
	v_lshl_add_u64 v[80:81], v[82:83], 2, s[62:63]
	v_fmamk_f32 v83, v195, 0x3aaaaaab, v134
	v_cmp_gt_f32_e32 vcc, s13, v83
	v_mul_f32_e32 v85, 0x4b800000, v83
	s_nop 0
	v_cndmask_b32_e32 v83, v83, v85, vcc
	v_rsq_f32_e32 v83, v83
	s_nop 0
	v_mul_f32_e32 v85, 0x45800000, v83
	v_cndmask_b32_e32 v83, v83, v85, vcc
	v_mul_f32_e32 v86, 0x3e16c740, v83
	v_pk_mul_f32 v[78:79], v[78:79], v[86:87] op_sel_hi:[1,0]
	v_pk_mul_f32 v[76:77], v[76:77], v[86:87] op_sel_hi:[1,0]
	v_pk_mul_f32 v[74:75], v[74:75], v[86:87] op_sel_hi:[1,0]
	v_pk_mul_f32 v[86:87], v[72:73], v[86:87] op_sel_hi:[1,0]
	v_mov_b64_e32 v[72:73], s[60:61]
	v_mad_i64_i32 v[72:73], s[0:1], v82, s78, v[72:73]
	v_lshl_add_u64 v[72:73], s[68:69], 1, v[72:73]
	v_lshl_add_u64 v[72:73], v[72:73], 0, v[132:133]
	v_cvt_pk_bf16_f32 v76, v76, v77
	v_cvt_pk_bf16_f32 v77, v78, v79
	s_and_b64 vcc, exec, s[44:45]
	v_cvt_pk_bf16_f32 v78, v86, v87
	v_cvt_pk_bf16_f32 v79, v74, v75
	global_store_dwordx2 v[72:73], v[76:77], off
	global_store_dwordx2 v[72:73], v[78:79], off offset:32
	s_cbranch_vccnz .LBB0_141
	v_mov_b64_e32 v[74:75], v[224:225]
	v_mov_b64_e32 v[76:77], v[226:227]
	s_nop 0
	v_mov_b64_e32 v[82:83], v[228:229]
	v_mov_b64_e32 v[84:85], v[230:231]
	v_mov_b32_e32 v78, v74
	v_mov_b32_e32 v79, v76
	v_mov_b32_e32 v76, v75
	v_mul_f32_e32 v74, v70, v82
	v_mul_f32_e32 v86, v66, v83
	v_mul_f32_e32 v88, v70, v83
	v_mul_f32_e32 v82, v66, v82
	v_mov_b32_e32 v66, v71
	v_mov_b32_e32 v70, v67
	v_pk_mul_f32 v[90:91], v[64:65], v[76:77]
	v_pk_mul_f32 v[66:67], v[66:67], v[84:85]
	v_pk_mul_f32 v[70:71], v[70:71], v[84:85]
	v_pk_mul_f32 v[64:65], v[64:65], v[78:79]
	v_mov_b32_e32 v75, v66
	v_mov_b32_e32 v87, v67
	v_pk_fma_f32 v[78:79], v[68:69], v[78:79], v[90:91] neg_lo:[0,0,1] neg_hi:[0,0,1]
	v_mov_b32_e32 v89, v71
	v_mov_b32_e32 v83, v70
	v_pk_fma_f32 v[64:65], v[68:69], v[76:77], v[64:65]
	v_pk_add_f32 v[70:71], v[74:75], v[86:87] neg_lo:[0,1] neg_hi:[0,1]
	v_pk_add_f32 v[66:67], v[88:89], v[82:83]
	v_mov_b32_e32 v68, v78
	v_mov_b32_e32 v69, v79
; __device__ __forceinline__ unsigned pkbf(float lo, float hi) { f2_t v = {lo, hi}; return __builtin_bit_cast(unsigned, __builtin_convertvector(v, bf2_t)); }
;     __device__ __forceinline__ void operator()(const f32x4 (&acc)[2][2][4][2], const Unit& u, int wr, int wc, int fr, int fq) const {
;     ...
;             for (int m = 0; m < 4; ++m) { const int row = row0 + ai * HALF + m * 16; const int pos = row < 65536 ? (row & 2047) : 4096 + ((row - 65536) & 31);
; #pragma unroll
;                 for (int bj = 0; bj < 2; ++bj) { const int c0 = u.pn * BM + bj * HALF + wc * 32; f32x4 a = acc[ai][bj][m][0], b = acc[ai][bj][m][1];
;                     if ((c0 % 96) == 64) {
; #pragma unroll
;                         for (int j = 0; j < 4; ++j) { const f2_t cs = tab[pos * 16 + 4 * fq + j]; const float x1 = a[j], x2 = b[j]; a[j] = x1 * cs.x - x2 * cs.y; b[j] = x1 * cs.y + x2 * cs.x; } }
;                     { const float qs = qscale * rsqrtf(ssq[row] * (1.0f / 768.0f) + 1e-6f); a = a * qs; b = b * qs; }
;                     bf16_t* p = O + (size_t)row * 768 + c0 + 4 * fq;
;                     u32x2 wa, wb; wa.x = pkbf(a[0], a[1]); wa.y = pkbf(a[2], a[3]); wb.x = pkbf(b[0], b[1]); wb.y = pkbf(b[2], b[3]);
;                     *(u32x2*)p = wa; *(u32x2*)(p + 16) = wb; } }
.LBB0_141:
	s_mov_b32 s0, 0xff80
	v_fmamk_f32 v74, v195, 0x3aaaaaab, v134
	v_cmp_gt_f32_e32 vcc, s13, v74
	v_mul_f32_e32 v75, 0x4b800000, v74
	s_nop 0
	v_cndmask_b32_e32 v74, v74, v75, vcc
	v_rsq_f32_e32 v74, v74
	s_nop 0
	v_mul_f32_e32 v75, 0x45800000, v74
	v_cndmask_b32_e32 v74, v74, v75, vcc
	v_mul_f32_e32 v74, 0x3e16c740, v74
	v_pk_mul_f32 v[70:71], v[70:71], v[74:75] op_sel_hi:[1,0]
	v_pk_mul_f32 v[68:69], v[68:69], v[74:75] op_sel_hi:[1,0]
	v_pk_mul_f32 v[66:67], v[66:67], v[74:75] op_sel_hi:[1,0]
	v_pk_mul_f32 v[64:65], v[64:65], v[74:75] op_sel_hi:[1,0]
	v_cvt_pk_bf16_f32 v68, v68, v69
	v_cvt_pk_bf16_f32 v69, v70, v71
	v_cvt_pk_bf16_f32 v64, v64, v65
	v_cvt_pk_bf16_f32 v65, v66, v67
	global_store_dwordx2 v[72:73], v[68:69], off offset:256
	global_store_dwordx2 v[72:73], v[64:65], off offset:288
	v_add_u32_e32 v65, 0x80, v148
	v_cmp_gt_i32_e32 vcc, s0, v148
	v_and_b32_e32 v64, 0x7cf, v65
	s_nop 0
	v_cndmask_b32_e32 v64, v151, v64, vcc
	v_lshl_or_b32 v64, v64, 4, v140
	s_and_b64 vcc, exec, s[42:43]
	v_lshlrev_b32_e32 v64, 3, v64
	global_load_dwordx4 v[200:203], v239, s[4:5]
	global_load_dwordx4 v[204:207], v239, s[4:5] offset:16
	v_add_u32_e32 v236, 0x800, v239
	global_load_dwordx4 v[208:211], v236, s[4:5]
	global_load_dwordx4 v[212:215], v236, s[4:5] offset:16
	v_add_u32_e32 v237, 0x1000, v239
	global_load_dwordx4 v[216:219], v237, s[4:5]
	global_load_dwordx4 v[220:223], v237, s[4:5] offset:16
	v_add_u32_e32 v238, 0x1800, v239
	global_load_dwordx4 v[224:227], v238, s[4:5]
	global_load_dwordx4 v[228:231], v238, s[4:5] offset:16
	s_waitcnt vmcnt(0)
	s_cbranch_vccnz .LBB0_143
	v_mov_b64_e32 v[66:67], v[200:201]
	v_mov_b64_e32 v[68:69], v[202:203]
	v_mov_b64_e32 v[70:71], v[204:205]
	v_mov_b64_e32 v[72:73], v[206:207]
	v_mov_b32_e32 v74, v66
	v_mov_b32_e32 v75, v68
	v_mov_b32_e32 v68, v67
	v_mul_f32_e32 v66, v62, v70
	v_mul_f32_e32 v76, v58, v71
	v_mul_f32_e32 v78, v62, v71
	v_mul_f32_e32 v70, v58, v70
	v_mov_b32_e32 v58, v63
	v_mov_b32_e32 v62, v59
	v_pk_mul_f32 v[80:81], v[56:57], v[68:69]
	v_pk_mul_f32 v[58:59], v[58:59], v[72:73]
	v_pk_mul_f32 v[62:63], v[62:63], v[72:73]
	v_pk_mul_f32 v[56:57], v[56:57], v[74:75]
	v_mov_b32_e32 v67, v58
	v_mov_b32_e32 v77, v59
	v_pk_fma_f32 v[72:73], v[60:61], v[74:75], v[80:81] neg_lo:[0,0,1] neg_hi:[0,0,1]
	v_mov_b32_e32 v79, v63
	v_mov_b32_e32 v71, v62
	v_pk_fma_f32 v[56:57], v[60:61], v[68:69], v[56:57]
	v_pk_add_f32 v[62:63], v[66:67], v[76:77] neg_lo:[0,1] neg_hi:[0,1]
	v_pk_add_f32 v[58:59], v[78:79], v[70:71]
	v_mov_b32_e32 v60, v72
	v_mov_b32_e32 v61, v73
.LBB0_143:
	v_fmamk_f32 v66, v196, 0x3aaaaaab, v134
	v_cmp_gt_f32_e32 vcc, s13, v66
	v_mul_f32_e32 v67, 0x4b800000, v66
	s_nop 0
	v_cndmask_b32_e32 v66, v66, v67, vcc
	v_rsq_f32_e32 v66, v66
	s_nop 0
	v_mul_f32_e32 v67, 0x45800000, v66
	v_cndmask_b32_e32 v66, v66, v67, vcc
	v_mul_f32_e32 v66, 0x3e16c740, v66
	v_pk_mul_f32 v[62:63], v[62:63], v[66:67] op_sel_hi:[1,0]
	v_pk_mul_f32 v[60:61], v[60:61], v[66:67] op_sel_hi:[1,0]
	v_pk_mul_f32 v[58:59], v[58:59], v[66:67] op_sel_hi:[1,0]
	v_pk_mul_f32 v[66:67], v[56:57], v[66:67] op_sel_hi:[1,0]
	v_mov_b64_e32 v[56:57], s[60:61]
	v_mad_i64_i32 v[56:57], s[0:1], v65, s78, v[56:57]
	v_lshl_add_u64 v[56:57], s[68:69], 1, v[56:57]
	v_lshl_add_u64 v[56:57], v[56:57], 0, v[132:133]
	v_cvt_pk_bf16_f32 v60, v60, v61
	v_cvt_pk_bf16_f32 v61, v62, v63
	s_and_b64 vcc, exec, s[44:45]
	v_cvt_pk_bf16_f32 v62, v66, v67
	v_cvt_pk_bf16_f32 v63, v58, v59
	global_store_dwordx2 v[56:57], v[60:61], off
	global_store_dwordx2 v[56:57], v[62:63], off offset:32
	s_cbranch_vccnz .LBB0_145
	v_mov_b64_e32 v[58:59], v[200:201]
	v_mov_b64_e32 v[60:61], v[202:203]
	s_nop 0
	v_mov_b64_e32 v[62:63], v[204:205]
	v_mov_b64_e32 v[64:65], v[206:207]
	v_mov_b32_e32 v66, v58
	v_mov_b32_e32 v67, v60
	v_mov_b32_e32 v60, v59
	v_mul_f32_e32 v58, v54, v62
	v_mul_f32_e32 v68, v50, v63
	v_mul_f32_e32 v70, v54, v63
	v_mul_f32_e32 v62, v50, v62
	v_mov_b32_e32 v50, v55
	v_mov_b32_e32 v54, v51
	v_pk_mul_f32 v[72:73], v[48:49], v[60:61]
	v_pk_mul_f32 v[50:51], v[50:51], v[64:65]
	v_pk_mul_f32 v[54:55], v[54:55], v[64:65]
	v_pk_mul_f32 v[48:49], v[48:49], v[66:67]
	v_mov_b32_e32 v59, v50
	v_mov_b32_e32 v69, v51
	v_pk_fma_f32 v[64:65], v[52:53], v[66:67], v[72:73] neg_lo:[0,0,1] neg_hi:[0,0,1]
	v_mov_b32_e32 v71, v55
	v_mov_b32_e32 v63, v54
	v_pk_fma_f32 v[48:49], v[52:53], v[60:61], v[48:49]
	v_pk_add_f32 v[54:55], v[58:59], v[68:69] neg_lo:[0,1] neg_hi:[0,1]
	v_pk_add_f32 v[50:51], v[70:71], v[62:63]
	v_mov_b32_e32 v52, v64
	v_mov_b32_e32 v53, v65
.LBB0_145:
	s_mov_b32 s0, 0xff70
	v_fmamk_f32 v58, v196, 0x3aaaaaab, v134
	v_cmp_gt_f32_e32 vcc, s13, v58
	v_mul_f32_e32 v59, 0x4b800000, v58
	s_nop 0
	v_cndmask_b32_e32 v58, v58, v59, vcc
	v_rsq_f32_e32 v58, v58
	s_nop 0
	v_mul_f32_e32 v59, 0x45800000, v58
	v_cndmask_b32_e32 v58, v58, v59, vcc
	v_mul_f32_e32 v58, 0x3e16c740, v58
	v_pk_mul_f32 v[54:55], v[54:55], v[58:59] op_sel_hi:[1,0]
	v_pk_mul_f32 v[52:53], v[52:53], v[58:59] op_sel_hi:[1,0]
	v_pk_mul_f32 v[50:51], v[50:51], v[58:59] op_sel_hi:[1,0]
	v_pk_mul_f32 v[48:49], v[48:49], v[58:59] op_sel_hi:[1,0]
	v_cvt_pk_bf16_f32 v52, v52, v53
	v_cvt_pk_bf16_f32 v53, v54, v55
	v_cvt_pk_bf16_f32 v48, v48, v49
	v_cvt_pk_bf16_f32 v49, v50, v51
	global_store_dwordx2 v[56:57], v[52:53], off offset:256
	global_store_dwordx2 v[56:57], v[48:49], off offset:288
	v_add_u32_e32 v49, 0x90, v148
	v_cmp_gt_i32_e32 vcc, s0, v148
	v_and_b32_e32 v48, 0x7df, v49
	s_nop 0
	v_cndmask_b32_e32 v48, v152, v48, vcc
	v_lshl_or_b32 v48, v48, 4, v140
	s_and_b64 vcc, exec, s[42:43]
	v_lshlrev_b32_e32 v48, 3, v48
	s_cbranch_vccnz .LBB0_147
	v_mov_b64_e32 v[50:51], v[208:209]
	v_mov_b64_e32 v[52:53], v[210:211]
	v_mov_b64_e32 v[54:55], v[212:213]
	v_mov_b64_e32 v[56:57], v[214:215]
	v_mov_b32_e32 v58, v50
	v_mov_b32_e32 v59, v52
	v_mov_b32_e32 v52, v51
	v_mul_f32_e32 v50, v46, v54
	v_mul_f32_e32 v60, v42, v55
	v_mul_f32_e32 v62, v46, v55
	v_mul_f32_e32 v54, v42, v54
	v_mov_b32_e32 v42, v47
	v_mov_b32_e32 v46, v43
	v_pk_mul_f32 v[64:65], v[40:41], v[52:53]
	v_pk_mul_f32 v[42:43], v[42:43], v[56:57]
	v_pk_mul_f32 v[46:47], v[46:47], v[56:57]
	v_pk_mul_f32 v[40:41], v[40:41], v[58:59]
	v_mov_b32_e32 v51, v42
	v_mov_b32_e32 v61, v43
	v_pk_fma_f32 v[56:57], v[44:45], v[58:59], v[64:65] neg_lo:[0,0,1] neg_hi:[0,0,1]
	v_mov_b32_e32 v63, v47
	v_mov_b32_e32 v55, v46
	v_pk_fma_f32 v[40:41], v[44:45], v[52:53], v[40:41]
	v_pk_add_f32 v[46:47], v[50:51], v[60:61] neg_lo:[0,1] neg_hi:[0,1]
	v_pk_add_f32 v[42:43], v[62:63], v[54:55]
	v_mov_b32_e32 v44, v56
	v_mov_b32_e32 v45, v57
; __device__ __forceinline__ unsigned pkbf(float lo, float hi) { f2_t v = {lo, hi}; return __builtin_bit_cast(unsigned, __builtin_convertvector(v, bf2_t)); }
;     __device__ __forceinline__ void operator()(const f32x4 (&acc)[2][2][4][2], const Unit& u, int wr, int wc, int fr, int fq) const {
;     ...
;             for (int m = 0; m < 4; ++m) { const int row = row0 + ai * HALF + m * 16; const int pos = row < 65536 ? (row & 2047) : 4096 + ((row - 65536) & 31);
; #pragma unroll
;                 for (int bj = 0; bj < 2; ++bj) { const int c0 = u.pn * BM + bj * HALF + wc * 32; f32x4 a = acc[ai][bj][m][0], b = acc[ai][bj][m][1];
;                     if ((c0 % 96) == 64) {
; #pragma unroll
;                         for (int j = 0; j < 4; ++j) { const f2_t cs = tab[pos * 16 + 4 * fq + j]; const float x1 = a[j], x2 = b[j]; a[j] = x1 * cs.x - x2 * cs.y; b[j] = x1 * cs.y + x2 * cs.x; } }
;                     { const float qs = qscale * rsqrtf(ssq[row] * (1.0f / 768.0f) + 1e-6f); a = a * qs; b = b * qs; }
;                     bf16_t* p = O + (size_t)row * 768 + c0 + 4 * fq;
;                     u32x2 wa, wb; wa.x = pkbf(a[0], a[1]); wa.y = pkbf(a[2], a[3]); wb.x = pkbf(b[0], b[1]); wb.y = pkbf(b[2], b[3]);
;                     *(u32x2*)p = wa; *(u32x2*)(p + 16) = wb; } }
.LBB0_147:
	v_fmamk_f32 v50, v197, 0x3aaaaaab, v134
	v_cmp_gt_f32_e32 vcc, s13, v50
	v_mul_f32_e32 v51, 0x4b800000, v50
	s_nop 0
	v_cndmask_b32_e32 v50, v50, v51, vcc
	v_rsq_f32_e32 v50, v50
	s_nop 0
	v_mul_f32_e32 v51, 0x45800000, v50
	v_cndmask_b32_e32 v50, v50, v51, vcc
	v_mul_f32_e32 v50, 0x3e16c740, v50
	v_pk_mul_f32 v[46:47], v[46:47], v[50:51] op_sel_hi:[1,0]
	v_pk_mul_f32 v[44:45], v[44:45], v[50:51] op_sel_hi:[1,0]
	v_pk_mul_f32 v[42:43], v[42:43], v[50:51] op_sel_hi:[1,0]
	v_pk_mul_f32 v[50:51], v[40:41], v[50:51] op_sel_hi:[1,0]
	v_mov_b64_e32 v[40:41], s[60:61]
	v_mad_i64_i32 v[40:41], s[0:1], v49, s78, v[40:41]
	v_lshl_add_u64 v[40:41], s[68:69], 1, v[40:41]
	v_lshl_add_u64 v[40:41], v[40:41], 0, v[132:133]
	v_cvt_pk_bf16_f32 v44, v44, v45
	v_cvt_pk_bf16_f32 v45, v46, v47
	s_and_b64 vcc, exec, s[44:45]
	v_cvt_pk_bf16_f32 v46, v50, v51
	v_cvt_pk_bf16_f32 v47, v42, v43
	global_store_dwordx2 v[40:41], v[44:45], off
	global_store_dwordx2 v[40:41], v[46:47], off offset:32
	s_cbranch_vccnz .LBB0_149
	v_mov_b64_e32 v[42:43], v[208:209]
	v_mov_b64_e32 v[44:45], v[210:211]
	s_nop 0
	v_mov_b64_e32 v[46:47], v[212:213]
	v_mov_b64_e32 v[48:49], v[214:215]
	v_mov_b32_e32 v50, v42
	v_mov_b32_e32 v51, v44
	v_mov_b32_e32 v44, v43
	v_mul_f32_e32 v42, v38, v46
	v_mul_f32_e32 v52, v34, v47
	v_mul_f32_e32 v54, v38, v47
	v_mul_f32_e32 v46, v34, v46
	v_mov_b32_e32 v34, v39
	v_mov_b32_e32 v38, v35
	v_pk_mul_f32 v[56:57], v[32:33], v[44:45]
	v_pk_mul_f32 v[34:35], v[34:35], v[48:49]
	v_pk_mul_f32 v[38:39], v[38:39], v[48:49]
	v_pk_mul_f32 v[32:33], v[32:33], v[50:51]
	v_mov_b32_e32 v43, v34
	v_mov_b32_e32 v53, v35
	v_pk_fma_f32 v[48:49], v[36:37], v[50:51], v[56:57] neg_lo:[0,0,1] neg_hi:[0,0,1]
	v_mov_b32_e32 v55, v39
	v_mov_b32_e32 v47, v38
	v_pk_fma_f32 v[32:33], v[36:37], v[44:45], v[32:33]
	v_pk_add_f32 v[38:39], v[42:43], v[52:53] neg_lo:[0,1] neg_hi:[0,1]
	v_pk_add_f32 v[34:35], v[54:55], v[46:47]
	v_mov_b32_e32 v36, v48
	v_mov_b32_e32 v37, v49
.LBB0_149:
	s_mov_b32 s0, 0xff60
	v_fmamk_f32 v42, v197, 0x3aaaaaab, v134
	v_cmp_gt_f32_e32 vcc, s13, v42
	v_mul_f32_e32 v43, 0x4b800000, v42
	s_nop 0
	v_cndmask_b32_e32 v42, v42, v43, vcc
	v_rsq_f32_e32 v42, v42
	s_nop 0
	v_mul_f32_e32 v43, 0x45800000, v42
	v_cndmask_b32_e32 v42, v42, v43, vcc
	v_mul_f32_e32 v42, 0x3e16c740, v42
	v_pk_mul_f32 v[38:39], v[38:39], v[42:43] op_sel_hi:[1,0]
	v_pk_mul_f32 v[36:37], v[36:37], v[42:43] op_sel_hi:[1,0]
	v_pk_mul_f32 v[34:35], v[34:35], v[42:43] op_sel_hi:[1,0]
	v_pk_mul_f32 v[32:33], v[32:33], v[42:43] op_sel_hi:[1,0]
	v_cvt_pk_bf16_f32 v36, v36, v37
	v_cvt_pk_bf16_f32 v37, v38, v39
	v_cvt_pk_bf16_f32 v32, v32, v33
	v_cvt_pk_bf16_f32 v33, v34, v35
	global_store_dwordx2 v[40:41], v[36:37], off offset:256
	global_store_dwordx2 v[40:41], v[32:33], off offset:288
	v_add_u32_e32 v33, 0xa0, v148
	v_cmp_gt_i32_e32 vcc, s0, v148
	v_and_b32_e32 v32, 0x7ef, v33
	s_nop 0
	v_cndmask_b32_e32 v32, v151, v32, vcc
	v_lshl_or_b32 v32, v32, 4, v140
	s_and_b64 vcc, exec, s[42:43]
	v_lshlrev_b32_e32 v32, 3, v32
	s_cbranch_vccnz .LBB0_151
	v_mov_b64_e32 v[34:35], v[216:217]
	v_mov_b64_e32 v[36:37], v[218:219]
	v_mov_b64_e32 v[38:39], v[220:221]
	v_mov_b64_e32 v[40:41], v[222:223]
	v_mov_b32_e32 v42, v34
	v_mov_b32_e32 v43, v36
	v_mov_b32_e32 v36, v35
	v_mul_f32_e32 v34, v30, v38
	v_mul_f32_e32 v44, v26, v39
	v_mul_f32_e32 v46, v30, v39
	v_mul_f32_e32 v38, v26, v38
	v_mov_b32_e32 v26, v31
	v_mov_b32_e32 v30, v27
	v_pk_mul_f32 v[48:49], v[24:25], v[36:37]
	v_pk_mul_f32 v[26:27], v[26:27], v[40:41]
	v_pk_mul_f32 v[30:31], v[30:31], v[40:41]
	v_pk_mul_f32 v[24:25], v[24:25], v[42:43]
	v_mov_b32_e32 v35, v26
	v_mov_b32_e32 v45, v27
	v_pk_fma_f32 v[40:41], v[28:29], v[42:43], v[48:49] neg_lo:[0,0,1] neg_hi:[0,0,1]
	v_mov_b32_e32 v47, v31
	v_mov_b32_e32 v39, v30
	v_pk_fma_f32 v[24:25], v[28:29], v[36:37], v[24:25]
	v_pk_add_f32 v[30:31], v[34:35], v[44:45] neg_lo:[0,1] neg_hi:[0,1]
	v_pk_add_f32 v[26:27], v[46:47], v[38:39]
	v_mov_b32_e32 v28, v40
	v_mov_b32_e32 v29, v41
.LBB0_151:
	v_fmamk_f32 v34, v198, 0x3aaaaaab, v134
	v_cmp_gt_f32_e32 vcc, s13, v34
	v_mul_f32_e32 v35, 0x4b800000, v34
	s_nop 0
	v_cndmask_b32_e32 v34, v34, v35, vcc
	v_rsq_f32_e32 v34, v34
	s_nop 0
	v_mul_f32_e32 v35, 0x45800000, v34
	v_cndmask_b32_e32 v34, v34, v35, vcc
	v_mul_f32_e32 v34, 0x3e16c740, v34
	v_pk_mul_f32 v[30:31], v[30:31], v[34:35] op_sel_hi:[1,0]
	v_pk_mul_f32 v[28:29], v[28:29], v[34:35] op_sel_hi:[1,0]
	v_pk_mul_f32 v[26:27], v[26:27], v[34:35] op_sel_hi:[1,0]
	v_pk_mul_f32 v[34:35], v[24:25], v[34:35] op_sel_hi:[1,0]
	v_mov_b64_e32 v[24:25], s[60:61]
	v_mad_i64_i32 v[24:25], s[0:1], v33, s78, v[24:25]
	v_lshl_add_u64 v[24:25], s[68:69], 1, v[24:25]
	v_lshl_add_u64 v[24:25], v[24:25], 0, v[132:133]
	v_cvt_pk_bf16_f32 v28, v28, v29
	v_cvt_pk_bf16_f32 v29, v30, v31
	s_and_b64 vcc, exec, s[44:45]
	v_cvt_pk_bf16_f32 v30, v34, v35
	v_cvt_pk_bf16_f32 v31, v26, v27
	global_store_dwordx2 v[24:25], v[28:29], off
	global_store_dwordx2 v[24:25], v[30:31], off offset:32
	s_cbranch_vccnz .LBB0_153
	v_mov_b64_e32 v[26:27], v[216:217]
	v_mov_b64_e32 v[28:29], v[218:219]
	s_nop 0
	v_mov_b64_e32 v[30:31], v[220:221]
	v_mov_b64_e32 v[32:33], v[222:223]
	v_mov_b32_e32 v34, v26
	v_mov_b32_e32 v35, v28
	v_mov_b32_e32 v28, v27
	v_mul_f32_e32 v26, v22, v30
	v_mul_f32_e32 v36, v18, v31
	v_mul_f32_e32 v38, v22, v31
	v_mul_f32_e32 v30, v18, v30
	v_mov_b32_e32 v18, v23
	v_mov_b32_e32 v22, v19
	v_pk_mul_f32 v[40:41], v[16:17], v[28:29]
	v_pk_mul_f32 v[18:19], v[18:19], v[32:33]
	v_pk_mul_f32 v[22:23], v[22:23], v[32:33]
	v_pk_mul_f32 v[16:17], v[16:17], v[34:35]
	v_mov_b32_e32 v27, v18
	v_mov_b32_e32 v37, v19
	v_pk_fma_f32 v[32:33], v[20:21], v[34:35], v[40:41] neg_lo:[0,0,1] neg_hi:[0,0,1]
	v_mov_b32_e32 v39, v23
	v_mov_b32_e32 v31, v22
	v_pk_fma_f32 v[16:17], v[20:21], v[28:29], v[16:17]
	v_pk_add_f32 v[22:23], v[26:27], v[36:37] neg_lo:[0,1] neg_hi:[0,1]
	v_pk_add_f32 v[18:19], v[38:39], v[30:31]
	v_mov_b32_e32 v20, v32
	v_mov_b32_e32 v21, v33
; __device__ __forceinline__ unsigned pkbf(float lo, float hi) { f2_t v = {lo, hi}; return __builtin_bit_cast(unsigned, __builtin_convertvector(v, bf2_t)); }
;     __device__ __forceinline__ void operator()(const f32x4 (&acc)[2][2][4][2], const Unit& u, int wr, int wc, int fr, int fq) const {
;     ...
;             for (int m = 0; m < 4; ++m) { const int row = row0 + ai * HALF + m * 16; const int pos = row < 65536 ? (row & 2047) : 4096 + ((row - 65536) & 31);
; #pragma unroll
;                 for (int bj = 0; bj < 2; ++bj) { const int c0 = u.pn * BM + bj * HALF + wc * 32; f32x4 a = acc[ai][bj][m][0], b = acc[ai][bj][m][1];
;                     if ((c0 % 96) == 64) {
; #pragma unroll
;                         for (int j = 0; j < 4; ++j) { const f2_t cs = tab[pos * 16 + 4 * fq + j]; const float x1 = a[j], x2 = b[j]; a[j] = x1 * cs.x - x2 * cs.y; b[j] = x1 * cs.y + x2 * cs.x; } }
;                     { const float qs = qscale * rsqrtf(ssq[row] * (1.0f / 768.0f) + 1e-6f); a = a * qs; b = b * qs; }
;                     bf16_t* p = O + (size_t)row * 768 + c0 + 4 * fq;
;                     u32x2 wa, wb; wa.x = pkbf(a[0], a[1]); wa.y = pkbf(a[2], a[3]); wb.x = pkbf(b[0], b[1]); wb.y = pkbf(b[2], b[3]);
;                     *(u32x2*)p = wa; *(u32x2*)(p + 16) = wb; } }
.LBB0_153:
	v_add_u32_e32 v26, 0xb0, v148
	s_mov_b32 s0, 0xff50
	s_and_b64 vcc, exec, s[42:43]
	v_cmp_gt_i32_e64 s[42:43], s0, v148
	v_fmamk_f32 v27, v198, 0x3aaaaaab, v134
	v_mul_f32_e32 v28, 0x4b800000, v27
	v_cmp_gt_f32_e64 s[46:47], s13, v27
	s_nop 1
	v_cndmask_b32_e64 v27, v27, v28, s[46:47]
	v_rsq_f32_e32 v27, v27
	v_and_b32_e32 v28, 0x7ff, v26
	v_cndmask_b32_e64 v28, v152, v28, s[42:43]
	v_lshl_or_b32 v29, v28, 4, v140
	v_mul_f32_e32 v28, 0x45800000, v27
	v_cndmask_b32_e64 v27, v27, v28, s[46:47]
	v_mul_f32_e32 v28, 0x3e16c740, v27
	v_pk_mul_f32 v[22:23], v[22:23], v[28:29] op_sel_hi:[1,0]
	v_pk_mul_f32 v[20:21], v[20:21], v[28:29] op_sel_hi:[1,0]
	v_pk_mul_f32 v[16:17], v[16:17], v[28:29] op_sel_hi:[1,0]
	v_pk_mul_f32 v[18:19], v[18:19], v[28:29] op_sel_hi:[1,0]
	v_cvt_pk_bf16_f32 v20, v20, v21
	v_cvt_pk_bf16_f32 v21, v22, v23
	v_cvt_pk_bf16_f32 v16, v16, v17
	v_cvt_pk_bf16_f32 v17, v18, v19
	global_store_dwordx2 v[24:25], v[20:21], off offset:256
	global_store_dwordx2 v[24:25], v[16:17], off offset:288
	v_lshlrev_b32_e32 v16, 3, v29
	s_cbranch_vccnz .LBB0_155
	v_mov_b64_e32 v[18:19], v[224:225]
	v_mov_b64_e32 v[20:21], v[226:227]
	v_mov_b64_e32 v[22:23], v[228:229]
	v_mov_b64_e32 v[24:25], v[230:231]
	v_mov_b32_e32 v28, v18
	v_mov_b32_e32 v29, v20
	v_mov_b32_e32 v20, v19
	v_mul_f32_e32 v18, v14, v22
	v_mul_f32_e32 v30, v10, v23
	v_mul_f32_e32 v32, v14, v23
	v_mul_f32_e32 v22, v10, v22
	v_mov_b32_e32 v10, v15
	v_mov_b32_e32 v14, v11
	v_pk_mul_f32 v[34:35], v[8:9], v[20:21]
	v_pk_mul_f32 v[10:11], v[10:11], v[24:25]
	v_pk_mul_f32 v[14:15], v[14:15], v[24:25]
	v_pk_mul_f32 v[8:9], v[8:9], v[28:29]
	v_mov_b32_e32 v19, v10
	v_mov_b32_e32 v31, v11
	v_pk_fma_f32 v[24:25], v[12:13], v[28:29], v[34:35] neg_lo:[0,0,1] neg_hi:[0,0,1]
	v_mov_b32_e32 v33, v15
	v_mov_b32_e32 v23, v14
	v_pk_fma_f32 v[8:9], v[12:13], v[20:21], v[8:9]
	v_pk_add_f32 v[14:15], v[18:19], v[30:31] neg_lo:[0,1] neg_hi:[0,1]
	v_pk_add_f32 v[10:11], v[32:33], v[22:23]
	v_mov_b32_e32 v12, v24
	v_mov_b32_e32 v13, v25
.LBB0_155:
	v_fmamk_f32 v17, v199, 0x3aaaaaab, v134
	v_cmp_gt_f32_e32 vcc, s13, v17
	v_mul_f32_e32 v18, 0x4b800000, v17
	s_nop 0
	v_cndmask_b32_e32 v17, v17, v18, vcc
	v_rsq_f32_e32 v17, v17
	s_nop 0
	v_mul_f32_e32 v18, 0x45800000, v17
	v_cndmask_b32_e32 v17, v17, v18, vcc
	v_mul_f32_e32 v18, 0x3e16c740, v17
	v_pk_mul_f32 v[14:15], v[14:15], v[18:19] op_sel_hi:[1,0]
	v_pk_mul_f32 v[12:13], v[12:13], v[18:19] op_sel_hi:[1,0]
	v_pk_mul_f32 v[10:11], v[10:11], v[18:19] op_sel_hi:[1,0]
	v_pk_mul_f32 v[18:19], v[8:9], v[18:19] op_sel_hi:[1,0]
	v_mov_b64_e32 v[8:9], s[60:61]
	v_mad_i64_i32 v[8:9], s[0:1], v26, s78, v[8:9]
	v_lshl_add_u64 v[8:9], s[68:69], 1, v[8:9]
	v_lshl_add_u64 v[8:9], v[8:9], 0, v[132:133]
	v_cvt_pk_bf16_f32 v12, v12, v13
	v_cvt_pk_bf16_f32 v13, v14, v15
	s_and_b64 vcc, exec, s[44:45]
	v_cvt_pk_bf16_f32 v14, v18, v19
	v_cvt_pk_bf16_f32 v15, v10, v11
	global_store_dwordx2 v[8:9], v[12:13], off
	global_store_dwordx2 v[8:9], v[14:15], off offset:32
	s_cbranch_vccnz .LBB0_157
	v_mov_b64_e32 v[10:11], v[224:225]
	v_mov_b64_e32 v[12:13], v[226:227]
	s_nop 0
	v_mov_b64_e32 v[14:15], v[228:229]
	v_mov_b64_e32 v[16:17], v[230:231]
	v_mov_b32_e32 v18, v10
	v_mov_b32_e32 v19, v12
	v_mov_b32_e32 v12, v11
	v_mul_f32_e32 v10, v6, v14
	v_mul_f32_e32 v20, v2, v15
	v_mul_f32_e32 v22, v6, v15
	v_mul_f32_e32 v14, v2, v14
	v_mov_b32_e32 v2, v7
	v_mov_b32_e32 v6, v3
	v_pk_mul_f32 v[24:25], v[0:1], v[12:13]
	v_pk_mul_f32 v[2:3], v[2:3], v[16:17]
	v_pk_mul_f32 v[6:7], v[6:7], v[16:17]
	v_pk_mul_f32 v[0:1], v[0:1], v[18:19]
	v_mov_b32_e32 v11, v2
	v_mov_b32_e32 v21, v3
	v_pk_fma_f32 v[16:17], v[4:5], v[18:19], v[24:25] neg_lo:[0,0,1] neg_hi:[0,0,1]
	v_mov_b32_e32 v23, v7
	v_mov_b32_e32 v15, v6
	v_pk_fma_f32 v[0:1], v[4:5], v[12:13], v[0:1]
	v_pk_add_f32 v[6:7], v[10:11], v[20:21] neg_lo:[0,1] neg_hi:[0,1]
	v_pk_add_f32 v[2:3], v[22:23], v[14:15]
	v_mov_b32_e32 v4, v16
	v_mov_b32_e32 v5, v17
.LBB0_157:
	s_and_b64 vcc, exec, s[40:41]
	s_mov_b64 s[40:41], -1
	v_fmamk_f32 v10, v199, 0x3aaaaaab, v134
	v_mul_f32_e32 v11, 0x4b800000, v10
	v_cmp_gt_f32_e64 s[42:43], s13, v10
	s_nop 1
	v_cndmask_b32_e64 v10, v10, v11, s[42:43]
	v_rsq_f32_e32 v10, v10
	s_nop 0
	v_mul_f32_e32 v11, 0x45800000, v10
	v_cndmask_b32_e64 v10, v10, v11, s[42:43]
	v_mul_f32_e32 v10, 0x3e16c740, v10
	v_pk_mul_f32 v[6:7], v[6:7], v[10:11] op_sel_hi:[1,0]
	v_pk_mul_f32 v[4:5], v[4:5], v[10:11] op_sel_hi:[1,0]
	v_pk_mul_f32 v[2:3], v[2:3], v[10:11] op_sel_hi:[1,0]
	v_pk_mul_f32 v[0:1], v[0:1], v[10:11] op_sel_hi:[1,0]
	v_cvt_pk_bf16_f32 v4, v4, v5
	v_cvt_pk_bf16_f32 v5, v6, v7
	v_cvt_pk_bf16_f32 v0, v0, v1
	v_cvt_pk_bf16_f32 v1, v2, v3
	global_store_dwordx2 v[8:9], v[4:5], off offset:256
	global_store_dwordx2 v[8:9], v[0:1], off offset:288
	s_cbranch_vccnz .LBB0_114
	s_andn2_b64 vcc, exec, s[20:21]
	s_cbranch_vccnz .LBB0_113
	s_barrier
	s_branch .LBB0_113
